# G5 interleaved B-fragment reads made LDS bank-conflict free (row parity flipped for lanes with bit4 set; packed halves swapped back with v_alignbit before the store)
# speedup vs baseline: 1.0173x; 1.0028x over previous
.LBB0_241:
	s_or_b64 exec, exec, s[0:1]
	v_add_u32_e32 v131, v130, v172
	ds_read_b128 v[132:135], v131
	ds_read_b128 v[142:145], v131 offset:4096
	ds_read_b128 v[146:149], v131 offset:8192
	ds_read_b128 v[150:153], v131 offset:12288
	v_xad_u32 v131, v172, v233, v128
	ds_read_b128 v[154:157], v131 offset:32768
	v_xor_b32_e32 v230, 0x80, v131
	ds_read_b128 v[158:161], v230 offset:32768
	s_setprio 1
	s_waitcnt lgkmcnt(0)
	v_mfma_f32_32x32x16_bf16 v[112:127], v[132:135], v[154:157], v[112:127]
	v_mfma_f32_32x32x16_bf16 v[96:111], v[132:135], v[158:161], v[96:111]
	v_mfma_f32_32x32x16_bf16 v[80:95], v[142:145], v[154:157], v[80:95]
	v_mfma_f32_32x32x16_bf16 v[64:79], v[142:145], v[158:161], v[64:79]
	v_mfma_f32_32x32x16_bf16 v[48:63], v[146:149], v[154:157], v[48:63]
	v_mfma_f32_32x32x16_bf16 v[32:47], v[146:149], v[158:161], v[32:47]
	v_mfma_f32_32x32x16_bf16 v[16:31], v[150:153], v[154:157], v[16:31]
	v_mfma_f32_32x32x16_bf16 v[0:15], v[150:153], v[158:161], v[0:15]
	s_setprio 0
	v_add_u32_e32 v141, v130, v171
	ds_read_b128 v[130:133], v141
	ds_read_b128 v[134:137], v141 offset:4096
	ds_read_b128 v[142:145], v141 offset:8192
	ds_read_b128 v[146:149], v141 offset:12288
	v_xad_u32 v128, v171, v233, v128
	ds_read_b128 v[150:153], v128 offset:32768
	v_xor_b32_e32 v230, 0x80, v128
	ds_read_b128 v[154:157], v230 offset:32768
	s_setprio 1
	s_waitcnt lgkmcnt(0)
	v_mfma_f32_32x32x16_bf16 v[112:127], v[130:133], v[150:153], v[112:127]
	v_mfma_f32_32x32x16_bf16 v[96:111], v[130:133], v[154:157], v[96:111]
	v_mfma_f32_32x32x16_bf16 v[80:95], v[134:137], v[150:153], v[80:95]
	v_mfma_f32_32x32x16_bf16 v[64:79], v[134:137], v[154:157], v[64:79]
	v_mfma_f32_32x32x16_bf16 v[48:63], v[142:145], v[150:153], v[48:63]
	v_mfma_f32_32x32x16_bf16 v[32:47], v[142:145], v[154:157], v[32:47]
	v_mfma_f32_32x32x16_bf16 v[16:31], v[146:149], v[150:153], v[16:31]
	v_mfma_f32_32x32x16_bf16 v[0:15], v[146:149], v[154:157], v[0:15]
	s_setprio 0
	v_add_u32_e32 v136, v170, v168
	v_and_b32_e32 v130, 31, v224
	v_and_b32_e32 v131, 0xc0, v224
	v_lshl_or_b32 v130, v130, 1, v131
	v_or_b32_e32 v130, v130, v169
	v_lshlrev_b32_e32 v136, 13, v136
	v_lshl_add_u32 v136, v130, 1, v136
	v_and_b32_e32 v131, 16, v224
	v_max_f32_e32 v112, v112, v112
	v_max_f32_e32 v96, v96, v96
	v_max_f32_e32 v112, 0, v112
	v_max_f32_e32 v96, 0, v96
	v_mul_f32_e32 v112, v112, v112
	v_mul_f32_e32 v96, v96, v96
	s_mov_b32 s0, s42
	s_mov_b32 s1, s43
	v_cvt_pk_bf16_f32 v112, v112, v96
	v_alignbit_b32 v112, v112, v112, v131
	global_store_dword v136, v112, s[0:1]
	v_max_f32_e32 v113, v113, v113
	v_max_f32_e32 v97, v97, v97
	v_max_f32_e32 v113, 0, v113
	v_max_f32_e32 v97, 0, v97
	v_mul_f32_e32 v113, v113, v113
	v_mul_f32_e32 v97, v97, v97
	s_add_u32 s0, s42, 0x2000
	s_addc_u32 s1, s43, 0
	v_cvt_pk_bf16_f32 v113, v113, v97
	v_alignbit_b32 v113, v113, v113, v131
	global_store_dword v136, v113, s[0:1]
	v_max_f32_e32 v114, v114, v114
	v_max_f32_e32 v98, v98, v98
	v_max_f32_e32 v114, 0, v114
	v_max_f32_e32 v98, 0, v98
	v_mul_f32_e32 v114, v114, v114
	v_mul_f32_e32 v98, v98, v98
	s_add_u32 s0, s42, 0x4000
	s_addc_u32 s1, s43, 0
	v_cvt_pk_bf16_f32 v114, v114, v98
	v_alignbit_b32 v114, v114, v114, v131
	global_store_dword v136, v114, s[0:1]
	v_max_f32_e32 v115, v115, v115
	v_max_f32_e32 v99, v99, v99
	v_max_f32_e32 v115, 0, v115
	v_max_f32_e32 v99, 0, v99
	v_mul_f32_e32 v115, v115, v115
	v_mul_f32_e32 v99, v99, v99
	s_add_u32 s0, s42, 0x6000
	s_addc_u32 s1, s43, 0
	v_cvt_pk_bf16_f32 v115, v115, v99
	v_alignbit_b32 v115, v115, v115, v131
	global_store_dword v136, v115, s[0:1]
	v_max_f32_e32 v116, v116, v116
	v_max_f32_e32 v100, v100, v100
	v_max_f32_e32 v116, 0, v116
	v_max_f32_e32 v100, 0, v100
	v_mul_f32_e32 v116, v116, v116
	v_mul_f32_e32 v100, v100, v100
	s_add_u32 s0, s42, 0x10000
	s_addc_u32 s1, s43, 0
	v_cvt_pk_bf16_f32 v116, v116, v100
	v_alignbit_b32 v116, v116, v116, v131
	global_store_dword v136, v116, s[0:1]
	v_max_f32_e32 v117, v117, v117
	v_max_f32_e32 v101, v101, v101
	v_max_f32_e32 v117, 0, v117
	v_max_f32_e32 v101, 0, v101
	v_mul_f32_e32 v117, v117, v117
	v_mul_f32_e32 v101, v101, v101
	s_add_u32 s0, s42, 0x12000
	s_addc_u32 s1, s43, 0
	v_cvt_pk_bf16_f32 v117, v117, v101
	v_alignbit_b32 v117, v117, v117, v131
	global_store_dword v136, v117, s[0:1]
	v_max_f32_e32 v118, v118, v118
	v_max_f32_e32 v102, v102, v102
	v_max_f32_e32 v118, 0, v118
	v_max_f32_e32 v102, 0, v102
	v_mul_f32_e32 v118, v118, v118
	v_mul_f32_e32 v102, v102, v102
	s_add_u32 s0, s42, 0x14000
	s_addc_u32 s1, s43, 0
	v_cvt_pk_bf16_f32 v118, v118, v102
	v_alignbit_b32 v118, v118, v118, v131
	global_store_dword v136, v118, s[0:1]
	v_max_f32_e32 v119, v119, v119
	v_max_f32_e32 v103, v103, v103
	v_max_f32_e32 v119, 0, v119
	v_max_f32_e32 v103, 0, v103
	v_mul_f32_e32 v119, v119, v119
	v_mul_f32_e32 v103, v103, v103
	s_add_u32 s0, s42, 0x16000
	s_addc_u32 s1, s43, 0
	v_cvt_pk_bf16_f32 v119, v119, v103
	v_alignbit_b32 v119, v119, v119, v131
	global_store_dword v136, v119, s[0:1]
	v_max_f32_e32 v120, v120, v120
	v_max_f32_e32 v104, v104, v104
	v_max_f32_e32 v120, 0, v120
	v_max_f32_e32 v104, 0, v104
	v_mul_f32_e32 v120, v120, v120
	v_mul_f32_e32 v104, v104, v104
	s_add_u32 s0, s42, 0x20000
	s_addc_u32 s1, s43, 0
	v_cvt_pk_bf16_f32 v120, v120, v104
	v_alignbit_b32 v120, v120, v120, v131
	global_store_dword v136, v120, s[0:1]
	v_max_f32_e32 v121, v121, v121
	v_max_f32_e32 v105, v105, v105
	v_max_f32_e32 v121, 0, v121
	v_max_f32_e32 v105, 0, v105
	v_mul_f32_e32 v121, v121, v121
	v_mul_f32_e32 v105, v105, v105
	s_add_u32 s0, s42, 0x22000
	s_addc_u32 s1, s43, 0
	v_cvt_pk_bf16_f32 v121, v121, v105
	v_alignbit_b32 v121, v121, v121, v131
	global_store_dword v136, v121, s[0:1]
	v_max_f32_e32 v122, v122, v122
	v_max_f32_e32 v106, v106, v106
	v_max_f32_e32 v122, 0, v122
	v_max_f32_e32 v106, 0, v106
	v_mul_f32_e32 v122, v122, v122
	v_mul_f32_e32 v106, v106, v106
	s_add_u32 s0, s42, 0x24000
	s_addc_u32 s1, s43, 0
	v_cvt_pk_bf16_f32 v122, v122, v106
	v_alignbit_b32 v122, v122, v122, v131
	global_store_dword v136, v122, s[0:1]
	v_max_f32_e32 v123, v123, v123
	v_max_f32_e32 v107, v107, v107
	v_max_f32_e32 v123, 0, v123
	v_max_f32_e32 v107, 0, v107
	v_mul_f32_e32 v123, v123, v123
	v_mul_f32_e32 v107, v107, v107
	s_add_u32 s0, s42, 0x26000
	s_addc_u32 s1, s43, 0
	v_cvt_pk_bf16_f32 v123, v123, v107
	v_alignbit_b32 v123, v123, v123, v131
	global_store_dword v136, v123, s[0:1]
	v_max_f32_e32 v124, v124, v124
	v_max_f32_e32 v108, v108, v108
	v_max_f32_e32 v124, 0, v124
	v_max_f32_e32 v108, 0, v108
	v_mul_f32_e32 v124, v124, v124
	v_mul_f32_e32 v108, v108, v108
	s_add_u32 s0, s42, 0x30000
	s_addc_u32 s1, s43, 0
	v_cvt_pk_bf16_f32 v124, v124, v108
	v_alignbit_b32 v124, v124, v124, v131
	global_store_dword v136, v124, s[0:1]
	v_max_f32_e32 v125, v125, v125
	v_max_f32_e32 v109, v109, v109
	v_max_f32_e32 v125, 0, v125
	v_max_f32_e32 v109, 0, v109
	v_mul_f32_e32 v125, v125, v125
	v_mul_f32_e32 v109, v109, v109
	s_add_u32 s0, s42, 0x32000
	s_addc_u32 s1, s43, 0
	v_cvt_pk_bf16_f32 v125, v125, v109
	v_alignbit_b32 v125, v125, v125, v131
	global_store_dword v136, v125, s[0:1]
	v_max_f32_e32 v126, v126, v126
	v_max_f32_e32 v110, v110, v110
	v_max_f32_e32 v126, 0, v126
	v_max_f32_e32 v110, 0, v110
	v_mul_f32_e32 v126, v126, v126
	v_mul_f32_e32 v110, v110, v110
	s_add_u32 s0, s42, 0x34000
	s_addc_u32 s1, s43, 0
	v_cvt_pk_bf16_f32 v126, v126, v110
	v_alignbit_b32 v126, v126, v126, v131
	global_store_dword v136, v126, s[0:1]
	v_max_f32_e32 v127, v127, v127
	v_max_f32_e32 v111, v111, v111
	v_max_f32_e32 v127, 0, v127
	v_max_f32_e32 v111, 0, v111
	v_mul_f32_e32 v127, v127, v127
	v_mul_f32_e32 v111, v111, v111
	s_add_u32 s0, s42, 0x36000
	s_addc_u32 s1, s43, 0
	v_cvt_pk_bf16_f32 v127, v127, v111
	v_alignbit_b32 v127, v127, v127, v131
	global_store_dword v136, v127, s[0:1]
	v_max_f32_e32 v80, v80, v80
	v_max_f32_e32 v64, v64, v64
	v_max_f32_e32 v80, 0, v80
	v_max_f32_e32 v64, 0, v64
	v_mul_f32_e32 v80, v80, v80
	v_mul_f32_e32 v64, v64, v64
	s_add_u32 s0, s42, 0x40000
	s_addc_u32 s1, s43, 0
	v_cvt_pk_bf16_f32 v80, v80, v64
	v_alignbit_b32 v80, v80, v80, v131
	global_store_dword v136, v80, s[0:1]
	v_max_f32_e32 v81, v81, v81
	v_max_f32_e32 v65, v65, v65
	v_max_f32_e32 v81, 0, v81
	v_max_f32_e32 v65, 0, v65
	v_mul_f32_e32 v81, v81, v81
	v_mul_f32_e32 v65, v65, v65
	s_add_u32 s0, s42, 0x42000
	s_addc_u32 s1, s43, 0
	v_cvt_pk_bf16_f32 v81, v81, v65
	v_alignbit_b32 v81, v81, v81, v131
	global_store_dword v136, v81, s[0:1]
	v_max_f32_e32 v82, v82, v82
	v_max_f32_e32 v66, v66, v66
	v_max_f32_e32 v82, 0, v82
	v_max_f32_e32 v66, 0, v66
	v_mul_f32_e32 v82, v82, v82
	v_mul_f32_e32 v66, v66, v66
	s_add_u32 s0, s42, 0x44000
	s_addc_u32 s1, s43, 0
	v_cvt_pk_bf16_f32 v82, v82, v66
	v_alignbit_b32 v82, v82, v82, v131
	global_store_dword v136, v82, s[0:1]
	v_max_f32_e32 v83, v83, v83
	v_max_f32_e32 v67, v67, v67
	v_max_f32_e32 v83, 0, v83
	v_max_f32_e32 v67, 0, v67
	v_mul_f32_e32 v83, v83, v83
	v_mul_f32_e32 v67, v67, v67
	s_add_u32 s0, s42, 0x46000
	s_addc_u32 s1, s43, 0
	v_cvt_pk_bf16_f32 v83, v83, v67
	v_alignbit_b32 v83, v83, v83, v131
	global_store_dword v136, v83, s[0:1]
	v_max_f32_e32 v84, v84, v84
	v_max_f32_e32 v68, v68, v68
	v_max_f32_e32 v84, 0, v84
	v_max_f32_e32 v68, 0, v68
	v_mul_f32_e32 v84, v84, v84
	v_mul_f32_e32 v68, v68, v68
	s_add_u32 s0, s42, 0x50000
	s_addc_u32 s1, s43, 0
	v_cvt_pk_bf16_f32 v84, v84, v68
	v_alignbit_b32 v84, v84, v84, v131
	global_store_dword v136, v84, s[0:1]
	v_max_f32_e32 v85, v85, v85
	v_max_f32_e32 v69, v69, v69
	v_max_f32_e32 v85, 0, v85
	v_max_f32_e32 v69, 0, v69
	v_mul_f32_e32 v85, v85, v85
	v_mul_f32_e32 v69, v69, v69
	s_add_u32 s0, s42, 0x52000
	s_addc_u32 s1, s43, 0
	v_cvt_pk_bf16_f32 v85, v85, v69
	v_alignbit_b32 v85, v85, v85, v131
	global_store_dword v136, v85, s[0:1]
	v_max_f32_e32 v86, v86, v86
	v_max_f32_e32 v70, v70, v70
	v_max_f32_e32 v86, 0, v86
	v_max_f32_e32 v70, 0, v70
	v_mul_f32_e32 v86, v86, v86
	v_mul_f32_e32 v70, v70, v70
	s_add_u32 s0, s42, 0x54000
	s_addc_u32 s1, s43, 0
	v_cvt_pk_bf16_f32 v86, v86, v70
	v_alignbit_b32 v86, v86, v86, v131
	global_store_dword v136, v86, s[0:1]
	v_max_f32_e32 v87, v87, v87
	v_max_f32_e32 v71, v71, v71
	v_max_f32_e32 v87, 0, v87
	v_max_f32_e32 v71, 0, v71
	v_mul_f32_e32 v87, v87, v87
	v_mul_f32_e32 v71, v71, v71
	s_add_u32 s0, s42, 0x56000
	s_addc_u32 s1, s43, 0
	v_cvt_pk_bf16_f32 v87, v87, v71
	v_alignbit_b32 v87, v87, v87, v131
	global_store_dword v136, v87, s[0:1]
	v_max_f32_e32 v88, v88, v88
	v_max_f32_e32 v72, v72, v72
	v_max_f32_e32 v88, 0, v88
	v_max_f32_e32 v72, 0, v72
	v_mul_f32_e32 v88, v88, v88
	v_mul_f32_e32 v72, v72, v72
	s_add_u32 s0, s42, 0x60000
	s_addc_u32 s1, s43, 0
	v_cvt_pk_bf16_f32 v88, v88, v72
	v_alignbit_b32 v88, v88, v88, v131
	global_store_dword v136, v88, s[0:1]
	v_max_f32_e32 v89, v89, v89
	v_max_f32_e32 v73, v73, v73
	v_max_f32_e32 v89, 0, v89
	v_max_f32_e32 v73, 0, v73
	v_mul_f32_e32 v89, v89, v89
	v_mul_f32_e32 v73, v73, v73
	s_add_u32 s0, s42, 0x62000
	s_addc_u32 s1, s43, 0
	v_cvt_pk_bf16_f32 v89, v89, v73
	v_alignbit_b32 v89, v89, v89, v131
	global_store_dword v136, v89, s[0:1]
	v_max_f32_e32 v90, v90, v90
	v_max_f32_e32 v74, v74, v74
	v_max_f32_e32 v90, 0, v90
	v_max_f32_e32 v74, 0, v74
	v_mul_f32_e32 v90, v90, v90
	v_mul_f32_e32 v74, v74, v74
	s_add_u32 s0, s42, 0x64000
	s_addc_u32 s1, s43, 0
	v_cvt_pk_bf16_f32 v90, v90, v74
	v_alignbit_b32 v90, v90, v90, v131
	global_store_dword v136, v90, s[0:1]
	v_max_f32_e32 v91, v91, v91
	v_max_f32_e32 v75, v75, v75
	v_max_f32_e32 v91, 0, v91
	v_max_f32_e32 v75, 0, v75
	v_mul_f32_e32 v91, v91, v91
	v_mul_f32_e32 v75, v75, v75
	s_add_u32 s0, s42, 0x66000
	s_addc_u32 s1, s43, 0
	v_cvt_pk_bf16_f32 v91, v91, v75
	v_alignbit_b32 v91, v91, v91, v131
	global_store_dword v136, v91, s[0:1]
	v_max_f32_e32 v92, v92, v92
	v_max_f32_e32 v76, v76, v76
	v_max_f32_e32 v92, 0, v92
	v_max_f32_e32 v76, 0, v76
	v_mul_f32_e32 v92, v92, v92
	v_mul_f32_e32 v76, v76, v76
	s_add_u32 s0, s42, 0x70000
	s_addc_u32 s1, s43, 0
	v_cvt_pk_bf16_f32 v92, v92, v76
	v_alignbit_b32 v92, v92, v92, v131
	global_store_dword v136, v92, s[0:1]
	v_max_f32_e32 v93, v93, v93
	v_max_f32_e32 v77, v77, v77
	v_max_f32_e32 v93, 0, v93
	v_max_f32_e32 v77, 0, v77
	v_mul_f32_e32 v93, v93, v93
	v_mul_f32_e32 v77, v77, v77
	s_add_u32 s0, s42, 0x72000
	s_addc_u32 s1, s43, 0
	v_cvt_pk_bf16_f32 v93, v93, v77
	v_alignbit_b32 v93, v93, v93, v131
	global_store_dword v136, v93, s[0:1]
	v_max_f32_e32 v94, v94, v94
	v_max_f32_e32 v78, v78, v78
	v_max_f32_e32 v94, 0, v94
	v_max_f32_e32 v78, 0, v78
	v_mul_f32_e32 v94, v94, v94
	v_mul_f32_e32 v78, v78, v78
	s_add_u32 s0, s42, 0x74000
	s_addc_u32 s1, s43, 0
	v_cvt_pk_bf16_f32 v94, v94, v78
	v_alignbit_b32 v94, v94, v94, v131
	global_store_dword v136, v94, s[0:1]
	v_max_f32_e32 v95, v95, v95
	v_max_f32_e32 v79, v79, v79
	v_max_f32_e32 v95, 0, v95
	v_max_f32_e32 v79, 0, v79
	v_mul_f32_e32 v95, v95, v95
	v_mul_f32_e32 v79, v79, v79
	s_add_u32 s0, s42, 0x76000
	s_addc_u32 s1, s43, 0
	v_cvt_pk_bf16_f32 v95, v95, v79
	v_alignbit_b32 v95, v95, v95, v131
	global_store_dword v136, v95, s[0:1]
	v_max_f32_e32 v48, v48, v48
	v_max_f32_e32 v32, v32, v32
	v_max_f32_e32 v48, 0, v48
	v_max_f32_e32 v32, 0, v32
	v_mul_f32_e32 v48, v48, v48
	v_mul_f32_e32 v32, v32, v32
	s_add_u32 s0, s42, 0x80000
	s_addc_u32 s1, s43, 0
	v_cvt_pk_bf16_f32 v48, v48, v32
	v_alignbit_b32 v48, v48, v48, v131
	global_store_dword v136, v48, s[0:1]
	v_max_f32_e32 v49, v49, v49
	v_max_f32_e32 v33, v33, v33
	v_max_f32_e32 v49, 0, v49
	v_max_f32_e32 v33, 0, v33
	v_mul_f32_e32 v49, v49, v49
	v_mul_f32_e32 v33, v33, v33
	s_add_u32 s0, s42, 0x82000
	s_addc_u32 s1, s43, 0
	v_cvt_pk_bf16_f32 v49, v49, v33
	v_alignbit_b32 v49, v49, v49, v131
	global_store_dword v136, v49, s[0:1]
	v_max_f32_e32 v50, v50, v50
	v_max_f32_e32 v34, v34, v34
	v_max_f32_e32 v50, 0, v50
	v_max_f32_e32 v34, 0, v34
	v_mul_f32_e32 v50, v50, v50
	v_mul_f32_e32 v34, v34, v34
	s_add_u32 s0, s42, 0x84000
	s_addc_u32 s1, s43, 0
	v_cvt_pk_bf16_f32 v50, v50, v34
	v_alignbit_b32 v50, v50, v50, v131
	global_store_dword v136, v50, s[0:1]
	v_max_f32_e32 v51, v51, v51
	v_max_f32_e32 v35, v35, v35
	v_max_f32_e32 v51, 0, v51
	v_max_f32_e32 v35, 0, v35
	v_mul_f32_e32 v51, v51, v51
	v_mul_f32_e32 v35, v35, v35
	s_add_u32 s0, s42, 0x86000
	s_addc_u32 s1, s43, 0
	v_cvt_pk_bf16_f32 v51, v51, v35
	v_alignbit_b32 v51, v51, v51, v131
	global_store_dword v136, v51, s[0:1]
	v_max_f32_e32 v52, v52, v52
	v_max_f32_e32 v36, v36, v36
	v_max_f32_e32 v52, 0, v52
	v_max_f32_e32 v36, 0, v36
	v_mul_f32_e32 v52, v52, v52
	v_mul_f32_e32 v36, v36, v36
	s_add_u32 s0, s42, 0x90000
	s_addc_u32 s1, s43, 0
	v_cvt_pk_bf16_f32 v52, v52, v36
	v_alignbit_b32 v52, v52, v52, v131
	global_store_dword v136, v52, s[0:1]
	v_max_f32_e32 v53, v53, v53
	v_max_f32_e32 v37, v37, v37
	v_max_f32_e32 v53, 0, v53
	v_max_f32_e32 v37, 0, v37
	v_mul_f32_e32 v53, v53, v53
	v_mul_f32_e32 v37, v37, v37
	s_add_u32 s0, s42, 0x92000
	s_addc_u32 s1, s43, 0
	v_cvt_pk_bf16_f32 v53, v53, v37
	v_alignbit_b32 v53, v53, v53, v131
	global_store_dword v136, v53, s[0:1]
	v_max_f32_e32 v54, v54, v54
	v_max_f32_e32 v38, v38, v38
	v_max_f32_e32 v54, 0, v54
	v_max_f32_e32 v38, 0, v38
	v_mul_f32_e32 v54, v54, v54
	v_mul_f32_e32 v38, v38, v38
	s_add_u32 s0, s42, 0x94000
	s_addc_u32 s1, s43, 0
	v_cvt_pk_bf16_f32 v54, v54, v38
	v_alignbit_b32 v54, v54, v54, v131
	global_store_dword v136, v54, s[0:1]
	v_max_f32_e32 v55, v55, v55
	v_max_f32_e32 v39, v39, v39
	v_max_f32_e32 v55, 0, v55
	v_max_f32_e32 v39, 0, v39
	v_mul_f32_e32 v55, v55, v55
	v_mul_f32_e32 v39, v39, v39
	s_add_u32 s0, s42, 0x96000
	s_addc_u32 s1, s43, 0
	v_cvt_pk_bf16_f32 v55, v55, v39
	v_alignbit_b32 v55, v55, v55, v131
	global_store_dword v136, v55, s[0:1]
	v_max_f32_e32 v56, v56, v56
	v_max_f32_e32 v40, v40, v40
	v_max_f32_e32 v56, 0, v56
	v_max_f32_e32 v40, 0, v40
	v_mul_f32_e32 v56, v56, v56
	v_mul_f32_e32 v40, v40, v40
	s_add_u32 s0, s42, 0xa0000
	s_addc_u32 s1, s43, 0
	v_cvt_pk_bf16_f32 v56, v56, v40
	v_alignbit_b32 v56, v56, v56, v131
	global_store_dword v136, v56, s[0:1]
	v_max_f32_e32 v57, v57, v57
	v_max_f32_e32 v41, v41, v41
	v_max_f32_e32 v57, 0, v57
	v_max_f32_e32 v41, 0, v41
	v_mul_f32_e32 v57, v57, v57
	v_mul_f32_e32 v41, v41, v41
	s_add_u32 s0, s42, 0xa2000
	s_addc_u32 s1, s43, 0
	v_cvt_pk_bf16_f32 v57, v57, v41
	v_alignbit_b32 v57, v57, v57, v131
	global_store_dword v136, v57, s[0:1]
	v_max_f32_e32 v58, v58, v58
	v_max_f32_e32 v42, v42, v42
	v_max_f32_e32 v58, 0, v58
	v_max_f32_e32 v42, 0, v42
	v_mul_f32_e32 v58, v58, v58
	v_mul_f32_e32 v42, v42, v42
	s_add_u32 s0, s42, 0xa4000
	s_addc_u32 s1, s43, 0
	v_cvt_pk_bf16_f32 v58, v58, v42
	v_alignbit_b32 v58, v58, v58, v131
	global_store_dword v136, v58, s[0:1]
	v_max_f32_e32 v59, v59, v59
	v_max_f32_e32 v43, v43, v43
	v_max_f32_e32 v59, 0, v59
	v_max_f32_e32 v43, 0, v43
	v_mul_f32_e32 v59, v59, v59
	v_mul_f32_e32 v43, v43, v43
	s_add_u32 s0, s42, 0xa6000
	s_addc_u32 s1, s43, 0
	v_cvt_pk_bf16_f32 v59, v59, v43
	v_alignbit_b32 v59, v59, v59, v131
	global_store_dword v136, v59, s[0:1]
	v_max_f32_e32 v60, v60, v60
	v_max_f32_e32 v44, v44, v44
	v_max_f32_e32 v60, 0, v60
	v_max_f32_e32 v44, 0, v44
	v_mul_f32_e32 v60, v60, v60
	v_mul_f32_e32 v44, v44, v44
	s_add_u32 s0, s42, 0xb0000
	s_addc_u32 s1, s43, 0
	v_cvt_pk_bf16_f32 v60, v60, v44
	v_alignbit_b32 v60, v60, v60, v131
	global_store_dword v136, v60, s[0:1]
	v_max_f32_e32 v61, v61, v61
	v_max_f32_e32 v45, v45, v45
	v_max_f32_e32 v61, 0, v61
	v_max_f32_e32 v45, 0, v45
	v_mul_f32_e32 v61, v61, v61
	v_mul_f32_e32 v45, v45, v45
	s_add_u32 s0, s42, 0xb2000
	s_addc_u32 s1, s43, 0
	v_cvt_pk_bf16_f32 v61, v61, v45
	v_alignbit_b32 v61, v61, v61, v131
	global_store_dword v136, v61, s[0:1]
	v_max_f32_e32 v62, v62, v62
	v_max_f32_e32 v46, v46, v46
	v_max_f32_e32 v62, 0, v62
	v_max_f32_e32 v46, 0, v46
	v_mul_f32_e32 v62, v62, v62
	v_mul_f32_e32 v46, v46, v46
	s_add_u32 s0, s42, 0xb4000
	s_addc_u32 s1, s43, 0
	v_cvt_pk_bf16_f32 v62, v62, v46
	v_alignbit_b32 v62, v62, v62, v131
	global_store_dword v136, v62, s[0:1]
	v_max_f32_e32 v63, v63, v63
	v_max_f32_e32 v47, v47, v47
	v_max_f32_e32 v63, 0, v63
	v_max_f32_e32 v47, 0, v47
	v_mul_f32_e32 v63, v63, v63
	v_mul_f32_e32 v47, v47, v47
	s_add_u32 s0, s42, 0xb6000
	s_addc_u32 s1, s43, 0
	v_cvt_pk_bf16_f32 v63, v63, v47
	v_alignbit_b32 v63, v63, v63, v131
	global_store_dword v136, v63, s[0:1]
	v_max_f32_e32 v16, v16, v16
	v_max_f32_e32 v0, v0, v0
	v_max_f32_e32 v16, 0, v16
	v_max_f32_e32 v0, 0, v0
	v_mul_f32_e32 v16, v16, v16
	v_mul_f32_e32 v0, v0, v0
	s_add_u32 s0, s42, 0xc0000
	s_addc_u32 s1, s43, 0
	v_cvt_pk_bf16_f32 v16, v16, v0
	v_alignbit_b32 v16, v16, v16, v131
	global_store_dword v136, v16, s[0:1]
	v_max_f32_e32 v17, v17, v17
	v_max_f32_e32 v1, v1, v1
	v_max_f32_e32 v17, 0, v17
	v_max_f32_e32 v1, 0, v1
	v_mul_f32_e32 v17, v17, v17
	v_mul_f32_e32 v1, v1, v1
	s_add_u32 s0, s42, 0xc2000
	s_addc_u32 s1, s43, 0
	v_cvt_pk_bf16_f32 v17, v17, v1
	v_alignbit_b32 v17, v17, v17, v131
	global_store_dword v136, v17, s[0:1]
	v_max_f32_e32 v18, v18, v18
	v_max_f32_e32 v2, v2, v2
	v_max_f32_e32 v18, 0, v18
	v_max_f32_e32 v2, 0, v2
	v_mul_f32_e32 v18, v18, v18
	v_mul_f32_e32 v2, v2, v2
	s_add_u32 s0, s42, 0xc4000
	s_addc_u32 s1, s43, 0
	v_cvt_pk_bf16_f32 v18, v18, v2
	v_alignbit_b32 v18, v18, v18, v131
	global_store_dword v136, v18, s[0:1]
	v_max_f32_e32 v19, v19, v19
	v_max_f32_e32 v3, v3, v3
	v_max_f32_e32 v19, 0, v19
	v_max_f32_e32 v3, 0, v3
	v_mul_f32_e32 v19, v19, v19
	v_mul_f32_e32 v3, v3, v3
	s_add_u32 s0, s42, 0xc6000
	s_addc_u32 s1, s43, 0
	v_cvt_pk_bf16_f32 v19, v19, v3
	v_alignbit_b32 v19, v19, v19, v131
	global_store_dword v136, v19, s[0:1]
	v_max_f32_e32 v20, v20, v20
	v_max_f32_e32 v4, v4, v4
	v_max_f32_e32 v20, 0, v20
	v_max_f32_e32 v4, 0, v4
	v_mul_f32_e32 v20, v20, v20
	v_mul_f32_e32 v4, v4, v4
	s_add_u32 s0, s42, 0xd0000
	s_addc_u32 s1, s43, 0
	v_cvt_pk_bf16_f32 v20, v20, v4
	v_alignbit_b32 v20, v20, v20, v131
	global_store_dword v136, v20, s[0:1]
	v_max_f32_e32 v21, v21, v21
	v_max_f32_e32 v5, v5, v5
	v_max_f32_e32 v21, 0, v21
	v_max_f32_e32 v5, 0, v5
	v_mul_f32_e32 v21, v21, v21
	v_mul_f32_e32 v5, v5, v5
	s_add_u32 s0, s42, 0xd2000
	s_addc_u32 s1, s43, 0
	v_cvt_pk_bf16_f32 v21, v21, v5
	v_alignbit_b32 v21, v21, v21, v131
	global_store_dword v136, v21, s[0:1]
	v_max_f32_e32 v22, v22, v22
	v_max_f32_e32 v6, v6, v6
	v_max_f32_e32 v22, 0, v22
	v_max_f32_e32 v6, 0, v6
	v_mul_f32_e32 v22, v22, v22
	v_mul_f32_e32 v6, v6, v6
	s_add_u32 s0, s42, 0xd4000
	s_addc_u32 s1, s43, 0
	v_cvt_pk_bf16_f32 v22, v22, v6
	v_alignbit_b32 v22, v22, v22, v131
	global_store_dword v136, v22, s[0:1]
	v_max_f32_e32 v23, v23, v23
	v_max_f32_e32 v7, v7, v7
	v_max_f32_e32 v23, 0, v23
	v_max_f32_e32 v7, 0, v7
	v_mul_f32_e32 v23, v23, v23
	v_mul_f32_e32 v7, v7, v7
	s_add_u32 s0, s42, 0xd6000
	s_addc_u32 s1, s43, 0
	v_cvt_pk_bf16_f32 v23, v23, v7
	v_alignbit_b32 v23, v23, v23, v131
	global_store_dword v136, v23, s[0:1]
	v_max_f32_e32 v24, v24, v24
	v_max_f32_e32 v8, v8, v8
	v_max_f32_e32 v24, 0, v24
	v_max_f32_e32 v8, 0, v8
	v_mul_f32_e32 v24, v24, v24
	v_mul_f32_e32 v8, v8, v8
	s_add_u32 s0, s42, 0xe0000
	s_addc_u32 s1, s43, 0
	v_cvt_pk_bf16_f32 v24, v24, v8
	v_alignbit_b32 v24, v24, v24, v131
	global_store_dword v136, v24, s[0:1]
	v_max_f32_e32 v25, v25, v25
	v_max_f32_e32 v9, v9, v9
	v_max_f32_e32 v25, 0, v25
	v_max_f32_e32 v9, 0, v9
	v_mul_f32_e32 v25, v25, v25
	v_mul_f32_e32 v9, v9, v9
	s_add_u32 s0, s42, 0xe2000
	s_addc_u32 s1, s43, 0
	v_cvt_pk_bf16_f32 v25, v25, v9
	v_alignbit_b32 v25, v25, v25, v131
	global_store_dword v136, v25, s[0:1]
	v_max_f32_e32 v26, v26, v26
	v_max_f32_e32 v10, v10, v10
	v_max_f32_e32 v26, 0, v26
	v_max_f32_e32 v10, 0, v10
	v_mul_f32_e32 v26, v26, v26
	v_mul_f32_e32 v10, v10, v10
	s_add_u32 s0, s42, 0xe4000
	s_addc_u32 s1, s43, 0
	v_cvt_pk_bf16_f32 v26, v26, v10
	v_alignbit_b32 v26, v26, v26, v131
	global_store_dword v136, v26, s[0:1]
	v_max_f32_e32 v27, v27, v27
	v_max_f32_e32 v11, v11, v11
	v_max_f32_e32 v27, 0, v27
	v_max_f32_e32 v11, 0, v11
	v_mul_f32_e32 v27, v27, v27
	v_mul_f32_e32 v11, v11, v11
	s_add_u32 s0, s42, 0xe6000
	s_addc_u32 s1, s43, 0
	v_cvt_pk_bf16_f32 v27, v27, v11
	v_alignbit_b32 v27, v27, v27, v131
	global_store_dword v136, v27, s[0:1]
	v_max_f32_e32 v28, v28, v28
	v_max_f32_e32 v12, v12, v12
	v_max_f32_e32 v28, 0, v28
	v_max_f32_e32 v12, 0, v12
	v_mul_f32_e32 v28, v28, v28
	v_mul_f32_e32 v12, v12, v12
	s_add_u32 s0, s42, 0xf0000
	s_addc_u32 s1, s43, 0
	v_cvt_pk_bf16_f32 v28, v28, v12
	v_alignbit_b32 v28, v28, v28, v131
	global_store_dword v136, v28, s[0:1]
	v_max_f32_e32 v29, v29, v29
	v_max_f32_e32 v13, v13, v13
	v_max_f32_e32 v29, 0, v29
	v_max_f32_e32 v13, 0, v13
	v_mul_f32_e32 v29, v29, v29
	v_mul_f32_e32 v13, v13, v13
	s_add_u32 s0, s42, 0xf2000
	s_addc_u32 s1, s43, 0
	v_cvt_pk_bf16_f32 v29, v29, v13
	v_alignbit_b32 v29, v29, v29, v131
	global_store_dword v136, v29, s[0:1]
	v_max_f32_e32 v30, v30, v30
	v_max_f32_e32 v14, v14, v14
	v_max_f32_e32 v30, 0, v30
	v_max_f32_e32 v14, 0, v14
	v_mul_f32_e32 v30, v30, v30
	v_mul_f32_e32 v14, v14, v14
	s_add_u32 s0, s42, 0xf4000
	s_addc_u32 s1, s43, 0
	v_cvt_pk_bf16_f32 v30, v30, v14
	v_alignbit_b32 v30, v30, v30, v131
	global_store_dword v136, v30, s[0:1]
	v_max_f32_e32 v31, v31, v31
	v_max_f32_e32 v15, v15, v15
	v_max_f32_e32 v31, 0, v31
	v_max_f32_e32 v15, 0, v15
	v_mul_f32_e32 v31, v31, v31
	v_mul_f32_e32 v15, v15, v15
	s_add_u32 s0, s42, 0xf6000
	s_addc_u32 s1, s43, 0
	v_cvt_pk_bf16_f32 v31, v31, v15
	v_alignbit_b32 v31, v31, v31, v131
	global_store_dword v136, v31, s[0:1]
	s_andn2_b64 exec, exec, s[48:49]
	s_cbranch_execz .LBB0_254
.LBB0_242:
	v_mov_b32_e32 v32, v224
	v_mov_b32_e32 v170, v138
	v_and_b32_e32 v0, 31, v32
	v_lshrrev_b32_e32 v1, 1, v32
	v_and_or_b32 v0, v1, s59, v0
	v_lshlrev_b32_e32 v182, 7, v0
	v_lshlrev_b32_e32 v0, 7, v32
	v_and_b32_e32 v183, 0x6000, v0
	v_and_b32_e32 v233, 31, v32
	v_lshl_or_b32 v183, v233, 8, v183
	v_and_b32_e32 v233, 16, v32
	v_lshl_or_b32 v183, v233, 3, v183
	v_lshrrev_b32_e32 v233, 1, v32
	v_xor_b32_e32 v233, v233, v32
	v_and_b32_e32 v233, 7, v233
	v_lshlrev_b32_e32 v233, 4, v233
	v_lshrrev_b32_e32 v0, 5, v32
	v_bfe_u32 v2, v32, 1, 3
	v_bfe_u32 v1, v32, 5, 1
	v_bitop3_b32 v0, v0, v2, 1 bitop3:0x6c
	v_lshlrev_b32_e32 v184, 4, v0
	v_bitop3_b32 v0, v1, v2, 2 bitop3:0x36
	v_lshlrev_b32_e32 v181, 4, v0
	v_bitop3_b32 v0, v1, v2, 4 bitop3:0x36
	v_ashrrev_i32_e32 v188, 3, v32
	v_add_u32_e32 v3, 0x200, v32
	v_add_u32_e32 v4, 0x400, v32
	v_add_u32_e32 v5, 0x600, v32
	v_lshlrev_b32_e32 v172, 4, v0
	v_bitop3_b32 v0, v1, v2, 6 bitop3:0x36
	v_mov_b32_e32 v169, v140
	s_movk_i32 s0, 0xff
	v_lshrrev_b32_e32 v33, 4, v32
	v_ashrrev_i32_e32 v187, 3, v3
	v_ashrrev_i32_e32 v186, 3, v4
	v_ashrrev_i32_e32 v185, 3, v5
	v_lshrrev_b32_e32 v176, 3, v32
	v_lshrrev_b32_e32 v175, 3, v3
	v_lshrrev_b32_e32 v174, 3, v4
	v_lshrrev_b32_e32 v173, 3, v5
	v_lshlrev_b32_e32 v171, 4, v0
	v_add_u32_e32 v0, v188, v170
	v_cmp_gt_i32_e32 vcc, s73, v32
	v_cmp_lt_i32_e64 s[0:1], s0, v32
	v_xor_b32_e32 v132, v33, v32
	v_lshlrev_b32_e32 v180, 4, v32
	v_lshlrev_b32_e32 v178, 4, v4
	v_ashrrev_i32_e32 v1, 31, v0
	v_add_u32_e32 v2, v187, v170
	v_add_u32_e32 v4, v186, v170
	v_add_u32_e32 v6, v185, v170
	v_add_u32_e32 v8, v176, v170
	v_add_u32_e32 v10, v175, v170
	v_add_u32_e32 v12, v174, v170
	v_add_u32_e32 v14, v173, v170
	v_add_u32_e32 v16, v188, v169
	v_add_u32_e32 v18, v187, v169
	v_add_u32_e32 v20, v186, v169
	v_add_u32_e32 v22, v185, v169
	v_add_u32_e32 v24, v176, v169
	v_add_u32_e32 v26, v175, v169
	v_add_u32_e32 v28, v174, v169
	v_add_u32_e32 v30, v173, v169
	v_bitop3_b32 v32, v33, 7, v32 bitop3:0x48
	v_lshlrev_b32_e32 v179, 4, v3
	v_lshlrev_b32_e32 v177, 4, v5
	v_lshlrev_b64 v[0:1], 11, v[0:1]
	v_ashrrev_i32_e32 v3, 31, v2
	v_ashrrev_i32_e32 v5, 31, v4
	v_ashrrev_i32_e32 v7, 31, v6
	v_ashrrev_i32_e32 v9, 31, v8
	v_ashrrev_i32_e32 v11, 31, v10
	v_ashrrev_i32_e32 v13, 31, v12
	v_ashrrev_i32_e32 v15, 31, v14
	v_ashrrev_i32_e32 v17, 31, v16
	v_ashrrev_i32_e32 v19, 31, v18
	v_ashrrev_i32_e32 v21, 31, v20
	v_ashrrev_i32_e32 v23, 31, v22
	v_ashrrev_i32_e32 v25, 31, v24
	v_ashrrev_i32_e32 v27, 31, v26
	v_ashrrev_i32_e32 v29, 31, v28
	v_ashrrev_i32_e32 v31, 31, v30
	v_lshlrev_b32_e32 v32, 4, v32
	s_waitcnt vmcnt(0)
	v_lshlrev_b64 v[2:3], 11, v[2:3]
	v_lshlrev_b64 v[4:5], 11, v[4:5]
	v_lshlrev_b64 v[6:7], 11, v[6:7]
	v_lshlrev_b64 v[8:9], 11, v[8:9]
	v_lshlrev_b64 v[10:11], 11, v[10:11]
	v_lshlrev_b64 v[12:13], 11, v[12:13]
	v_lshlrev_b64 v[14:15], 11, v[14:15]
	v_lshlrev_b64 v[16:17], 11, v[16:17]
	v_lshlrev_b64 v[18:19], 11, v[18:19]
	v_lshlrev_b64 v[20:21], 11, v[20:21]
	v_lshlrev_b64 v[22:23], 11, v[22:23]
	v_lshlrev_b64 v[24:25], 11, v[24:25]
	v_lshlrev_b64 v[26:27], 11, v[26:27]
	v_lshlrev_b64 v[28:29], 11, v[28:29]
	v_lshlrev_b64 v[30:31], 11, v[30:31]
	v_or_b32_e32 v0, v0, v32
	v_lshl_add_u64 v[134:135], s[44:45], 0, v[0:1]
	v_or_b32_e32 v2, v2, v32
	v_or_b32_e32 v4, v4, v32
	v_or_b32_e32 v6, v6, v32
	v_or_b32_e32 v16, v16, v32
	v_or_b32_e32 v18, v18, v32
	v_or_b32_e32 v20, v20, v32
	v_or_b32_e32 v22, v22, v32
	v_or_b32_e32 v8, v8, v32
	v_or_b32_e32 v10, v10, v32
	v_or_b32_e32 v12, v12, v32
	v_or_b32_e32 v14, v14, v32
	v_or_b32_e32 v24, v24, v32
	v_or_b32_e32 v26, v26, v32
	v_or_b32_e32 v28, v28, v32
	v_or_b32_e32 v30, v30, v32
	v_mov_b32_e32 v0, 0
	v_mov_b32_e32 v128, v139
	v_lshl_add_u64 v[136:137], s[44:45], 0, v[2:3]
	v_lshl_add_u64 v[138:139], s[44:45], 0, v[4:5]
	v_lshl_add_u64 v[140:141], s[44:45], 0, v[6:7]
	v_lshl_add_u64 v[142:143], s[46:47], 0, v[16:17]
	v_lshl_add_u64 v[144:145], s[46:47], 0, v[18:19]
	v_lshl_add_u64 v[146:147], s[46:47], 0, v[20:21]
	v_lshl_add_u64 v[148:149], s[46:47], 0, v[22:23]
	v_lshl_add_u64 v[150:151], s[44:45], 0, v[8:9]
	v_lshl_add_u64 v[152:153], s[44:45], 0, v[10:11]
	v_lshl_add_u64 v[154:155], s[44:45], 0, v[12:13]
	v_lshl_add_u64 v[156:157], s[44:45], 0, v[14:15]
	v_lshl_add_u64 v[158:159], s[46:47], 0, v[24:25]
	v_lshl_add_u64 v[160:161], s[46:47], 0, v[26:27]
	v_lshl_add_u64 v[162:163], s[46:47], 0, v[28:29]
	v_lshl_add_u64 v[164:165], s[46:47], 0, v[30:31]
	s_mov_b64 s[4:5], 0
	v_mov_b32_e32 v1, v0
	v_mov_b32_e32 v2, v0
	v_mov_b32_e32 v3, v0
	v_mov_b32_e32 v4, v0
	v_mov_b32_e32 v5, v0
	v_mov_b32_e32 v6, v0
	v_mov_b32_e32 v7, v0
	v_mov_b32_e32 v8, v0
	v_mov_b32_e32 v9, v0
	v_mov_b32_e32 v10, v0
	v_mov_b32_e32 v11, v0
	v_mov_b32_e32 v12, v0
	v_mov_b32_e32 v13, v0
	v_mov_b32_e32 v14, v0
	v_mov_b32_e32 v15, v0
	v_mov_b32_e32 v16, v0
	v_mov_b32_e32 v17, v0
	v_mov_b32_e32 v18, v0
	v_mov_b32_e32 v19, v0
	v_mov_b32_e32 v20, v0
	v_mov_b32_e32 v21, v0
	v_mov_b32_e32 v22, v0
	v_mov_b32_e32 v23, v0
	v_mov_b32_e32 v24, v0
	v_mov_b32_e32 v25, v0
	v_mov_b32_e32 v26, v0
	v_mov_b32_e32 v27, v0
	v_mov_b32_e32 v28, v0
	v_mov_b32_e32 v29, v0
	v_mov_b32_e32 v30, v0
	v_mov_b32_e32 v31, v0
	v_mov_b32_e32 v32, v0
	v_mov_b32_e32 v33, v0
	v_mov_b32_e32 v34, v0
	v_mov_b32_e32 v35, v0
	v_mov_b32_e32 v36, v0
	v_mov_b32_e32 v37, v0
	v_mov_b32_e32 v38, v0
	v_mov_b32_e32 v39, v0
	v_mov_b32_e32 v40, v0
	v_mov_b32_e32 v41, v0
	v_mov_b32_e32 v42, v0
	v_mov_b32_e32 v43, v0
	v_mov_b32_e32 v44, v0
	v_mov_b32_e32 v45, v0
	v_mov_b32_e32 v46, v0
	v_mov_b32_e32 v47, v0
	v_mov_b32_e32 v48, v0
	v_mov_b32_e32 v49, v0
	v_mov_b32_e32 v50, v0
	v_mov_b32_e32 v51, v0
	v_mov_b32_e32 v52, v0
	v_mov_b32_e32 v53, v0
	v_mov_b32_e32 v54, v0
	v_mov_b32_e32 v55, v0
	v_mov_b32_e32 v56, v0
	v_mov_b32_e32 v57, v0
	v_mov_b32_e32 v58, v0
	v_mov_b32_e32 v59, v0
	v_mov_b32_e32 v60, v0
	v_mov_b32_e32 v61, v0
	v_mov_b32_e32 v62, v0
	v_mov_b32_e32 v63, v0
	v_mov_b32_e32 v64, v0
	v_mov_b32_e32 v65, v0
	v_mov_b32_e32 v66, v0
	v_mov_b32_e32 v67, v0
	v_mov_b32_e32 v68, v0
	v_mov_b32_e32 v69, v0
	v_mov_b32_e32 v70, v0
	v_mov_b32_e32 v71, v0
	v_mov_b32_e32 v72, v0
	v_mov_b32_e32 v73, v0
	v_mov_b32_e32 v74, v0
	v_mov_b32_e32 v75, v0
	v_mov_b32_e32 v76, v0
	v_mov_b32_e32 v77, v0
	v_mov_b32_e32 v78, v0
	v_mov_b32_e32 v79, v0
	v_mov_b32_e32 v80, v0
	v_mov_b32_e32 v81, v0
	v_mov_b32_e32 v82, v0
	v_mov_b32_e32 v83, v0
	v_mov_b32_e32 v84, v0
	v_mov_b32_e32 v85, v0
	v_mov_b32_e32 v86, v0
	v_mov_b32_e32 v87, v0
	v_mov_b32_e32 v88, v0
	v_mov_b32_e32 v89, v0
	v_mov_b32_e32 v90, v0
	v_mov_b32_e32 v91, v0
	v_mov_b32_e32 v92, v0
	v_mov_b32_e32 v93, v0
	v_mov_b32_e32 v94, v0
	v_mov_b32_e32 v95, v0
	v_mov_b32_e32 v96, v0
	v_mov_b32_e32 v97, v0
	v_mov_b32_e32 v98, v0
	v_mov_b32_e32 v99, v0
	v_mov_b32_e32 v100, v0
	v_mov_b32_e32 v101, v0
	v_mov_b32_e32 v102, v0
	v_mov_b32_e32 v103, v0
	v_mov_b32_e32 v104, v0
	v_mov_b32_e32 v105, v0
	v_mov_b32_e32 v106, v0
	v_mov_b32_e32 v107, v0
	v_mov_b32_e32 v108, v0
	v_mov_b32_e32 v109, v0
	v_mov_b32_e32 v110, v0
	v_mov_b32_e32 v111, v0
	v_mov_b32_e32 v112, v0
	v_mov_b32_e32 v113, v0
	v_mov_b32_e32 v114, v0
	v_mov_b32_e32 v115, v0
	v_mov_b32_e32 v116, v0
	v_mov_b32_e32 v117, v0
	v_mov_b32_e32 v118, v0
	v_mov_b32_e32 v119, v0
	v_mov_b32_e32 v120, v0
	v_mov_b32_e32 v121, v0
	v_mov_b32_e32 v122, v0
	v_mov_b32_e32 v123, v0
	v_mov_b32_e32 v124, v0
	v_mov_b32_e32 v125, v0
	v_mov_b32_e32 v126, v0
	v_mov_b32_e32 v127, v0
	s_waitcnt vmcnt(0)
	s_barrier
	s_lshl_b32 s13, s9, 16
	s_and_saveexec_b64 s[6:7], vcc
	s_cbranch_execz .LBB0_245
	s_branch .LBB0_244

.LBB0_245:
	s_or_b64 exec, exec, s[6:7]
	s_add_i32 s6, s13, 0
	v_add_u32_e32 v131, s6, v182
	v_add_u32_e32 v130, s6, v183
	v_add_u32_e32 v133, v131, v184
	v_xad_u32 v230, v184, v233, v130
	ds_read_b128 v[190:193], v133
	ds_read_b128 v[194:197], v133 offset:4096
	ds_read_b128 v[198:201], v133 offset:8192
	ds_read_b128 v[202:205], v133 offset:12288
	ds_read_b128 v[206:209], v230 offset:32768
	v_xor_b32_e32 v227, 0x80, v230
	ds_read_b128 v[210:213], v227 offset:32768
	v_add_u32_e32 v133, v131, v181
	v_xad_u32 v230, v181, v233, v130
	s_setprio 1
	s_waitcnt lgkmcnt(0)
	v_mfma_f32_32x32x16_bf16 v[112:127], v[190:193], v[206:209], v[112:127]
	ds_read_b128 v[214:217], v133
	v_mfma_f32_32x32x16_bf16 v[96:111], v[190:193], v[210:213], v[96:111]
	ds_read_b128 v[218:221], v133 offset:4096
	v_mfma_f32_32x32x16_bf16 v[80:95], v[194:197], v[206:209], v[80:95]
	ds_read_b128 v[234:237], v133 offset:8192
	v_mfma_f32_32x32x16_bf16 v[64:79], v[194:197], v[210:213], v[64:79]
	ds_read_b128 v[238:241], v133 offset:12288
	v_mfma_f32_32x32x16_bf16 v[48:63], v[198:201], v[206:209], v[48:63]
	ds_read_b128 v[242:245], v230 offset:32768
	v_mfma_f32_32x32x16_bf16 v[32:47], v[198:201], v[210:213], v[32:47]
	v_xor_b32_e32 v227, 0x80, v230
	ds_read_b128 v[246:249], v227 offset:32768
	v_mfma_f32_32x32x16_bf16 v[16:31], v[202:205], v[206:209], v[16:31]
	v_mfma_f32_32x32x16_bf16 v[0:15], v[202:205], v[210:213], v[0:15]
	s_setprio 0
	v_add_u32_e32 v133, v131, v172
	v_xad_u32 v230, v172, v233, v130
	s_setprio 1
	s_waitcnt lgkmcnt(0)
	v_mfma_f32_32x32x16_bf16 v[112:127], v[214:217], v[242:245], v[112:127]
	ds_read_b128 v[190:193], v133
	v_mfma_f32_32x32x16_bf16 v[96:111], v[214:217], v[246:249], v[96:111]
	ds_read_b128 v[194:197], v133 offset:4096
	v_mfma_f32_32x32x16_bf16 v[80:95], v[218:221], v[242:245], v[80:95]
	ds_read_b128 v[198:201], v133 offset:8192
	v_mfma_f32_32x32x16_bf16 v[64:79], v[218:221], v[246:249], v[64:79]
	ds_read_b128 v[202:205], v133 offset:12288
	v_mfma_f32_32x32x16_bf16 v[48:63], v[234:237], v[242:245], v[48:63]
	ds_read_b128 v[206:209], v230 offset:32768
	v_mfma_f32_32x32x16_bf16 v[32:47], v[234:237], v[246:249], v[32:47]
	v_xor_b32_e32 v227, 0x80, v230
	ds_read_b128 v[210:213], v227 offset:32768
	v_mfma_f32_32x32x16_bf16 v[16:31], v[238:241], v[242:245], v[16:31]
	v_mfma_f32_32x32x16_bf16 v[0:15], v[238:241], v[246:249], v[0:15]
	s_setprio 0
	s_and_saveexec_b64 s[6:7], s[0:1]
	s_cbranch_execz .LBB0_247
	s_xor_b32 s13, s13, 0x10000
	s_add_i32 s13, s13, 0
	v_add_u32_e32 v133, s13, v180
	v_add_u32_e32 v227, s13, v179
	v_readfirstlane_b32 s14, v133
	v_lshl_add_u64 v[228:229], v[150:151], 0, s[4:5]
	s_mov_b32 m0, s14
	v_readfirstlane_b32 s14, v227
	v_add_u32_e32 v222, s13, v178
	global_load_lds_dwordx4 v[228:229], off
	v_lshl_add_u64 v[228:229], v[152:153], 0, s[4:5]
	s_mov_b32 m0, s14
	v_readfirstlane_b32 s14, v222
	v_add_u32_e32 v223, s13, v177
	global_load_lds_dwordx4 v[228:229], off
	v_lshl_add_u64 v[228:229], v[154:155], 0, s[4:5]
	s_mov_b32 m0, s14
	v_readfirstlane_b32 s13, v223
	v_add_u32_e32 v133, 0x8000, v133
	global_load_lds_dwordx4 v[228:229], off
	v_lshl_add_u64 v[228:229], v[156:157], 0, s[4:5]
	s_mov_b32 m0, s13
	v_readfirstlane_b32 s13, v133
	v_add_u32_e32 v133, 0x8000, v227
	global_load_lds_dwordx4 v[228:229], off
	v_lshl_add_u64 v[228:229], v[158:159], 0, s[4:5]
	s_mov_b32 m0, s13
	v_readfirstlane_b32 s13, v133
	v_add_u32_e32 v133, 0x8000, v222
	global_load_lds_dwordx4 v[228:229], off
	v_lshl_add_u64 v[228:229], v[160:161], 0, s[4:5]
	s_mov_b32 m0, s13
	v_readfirstlane_b32 s13, v133
	v_add_u32_e32 v133, 0x8000, v223
	global_load_lds_dwordx4 v[228:229], off
	v_lshl_add_u64 v[228:229], v[162:163], 0, s[4:5]
	s_mov_b32 m0, s13
	v_readfirstlane_b32 s13, v133
	global_load_lds_dwordx4 v[228:229], off
	v_lshl_add_u64 v[228:229], v[164:165], 0, s[4:5]
	s_mov_b32 m0, s13
	s_nop 0
	global_load_lds_dwordx4 v[228:229], off
.LBB0_247:
	s_or_b64 exec, exec, s[6:7]
	v_add_u32_e32 v133, v131, v171
	v_xad_u32 v230, v171, v233, v130
	s_setprio 1
	s_waitcnt lgkmcnt(0)
	v_mfma_f32_32x32x16_bf16 v[112:127], v[190:193], v[206:209], v[112:127]
	ds_read_b128 v[214:217], v133
	v_mfma_f32_32x32x16_bf16 v[96:111], v[190:193], v[210:213], v[96:111]
	ds_read_b128 v[218:221], v133 offset:4096
	v_mfma_f32_32x32x16_bf16 v[80:95], v[194:197], v[206:209], v[80:95]
	ds_read_b128 v[234:237], v133 offset:8192
	v_mfma_f32_32x32x16_bf16 v[64:79], v[194:197], v[210:213], v[64:79]
	ds_read_b128 v[238:241], v133 offset:12288
	v_mfma_f32_32x32x16_bf16 v[48:63], v[198:201], v[206:209], v[48:63]
	ds_read_b128 v[242:245], v230 offset:32768
	v_mfma_f32_32x32x16_bf16 v[32:47], v[198:201], v[210:213], v[32:47]
	v_xor_b32_e32 v227, 0x80, v230
	ds_read_b128 v[246:249], v227 offset:32768
	v_mfma_f32_32x32x16_bf16 v[16:31], v[202:205], v[206:209], v[16:31]
	v_mfma_f32_32x32x16_bf16 v[0:15], v[202:205], v[210:213], v[0:15]
	s_setprio 0
	s_setprio 1
	s_waitcnt lgkmcnt(0)
	v_mfma_f32_32x32x16_bf16 v[112:127], v[214:217], v[242:245], v[112:127]
	v_mfma_f32_32x32x16_bf16 v[96:111], v[214:217], v[246:249], v[96:111]
	v_mfma_f32_32x32x16_bf16 v[80:95], v[218:221], v[242:245], v[80:95]
	v_mfma_f32_32x32x16_bf16 v[64:79], v[218:221], v[246:249], v[64:79]
	v_mfma_f32_32x32x16_bf16 v[48:63], v[234:237], v[242:245], v[48:63]
	v_mfma_f32_32x32x16_bf16 v[32:47], v[234:237], v[246:249], v[32:47]
	v_mfma_f32_32x32x16_bf16 v[16:31], v[238:241], v[242:245], v[16:31]
	v_mfma_f32_32x32x16_bf16 v[0:15], v[238:241], v[246:249], v[0:15]
	s_setprio 0
	s_xor_b32 s6, s9, 1
	s_waitcnt vmcnt(0)
	s_add_u32 s4, s4, 0x80
	s_addc_u32 s5, s5, 0
	s_cmpk_lg_i32 s4, 0x780
	s_waitcnt vmcnt(0)
	s_barrier
	s_cbranch_scc1 .LBB0_243
	v_add_u32_e32 v139, s8, v128
	s_movk_i32 s0, 0x5f
	v_cmp_lt_i32_e64 s[0:1], s0, v139
	s_mov_b32 s4, 0x2aaaaaab
	s_nop 0
	v_cndmask_b32_e64 v128, v139, v128, s[0:1]
	v_mul_hi_i32 v130, v128, s4
	v_lshrrev_b32_e32 v131, 31, v130
	v_add_u32_e32 v130, v130, v131
	v_mul_lo_u32 v131, v130, 6
	v_sub_u32_e32 v128, v128, v131
	v_add_lshl_u32 v138, v128, v166, 8
	v_lshlrev_b32_e32 v128, 4, v132
	v_and_b32_e32 v128, 0x70, v128
	s_xor_b64 s[4:5], vcc, -1
	v_lshl_add_u64 v[136:137], s[38:39], 0, v[128:129]
	v_lshl_add_u64 v[134:135], s[40:41], 0, v[128:129]
	v_lshlrev_b32_e32 v140, 8, v130
	s_nor_b64 s[4:5], s[4:5], s[0:1]
	s_and_saveexec_b64 s[14:15], s[4:5]
	s_xor_b64 s[4:5], exec, s[14:15]
	s_cbranch_execz .LBB0_250
	s_lshl_b32 s7, s6, 16
	s_xor_b32 s13, s7, 0x10000
	v_add_u32_e32 v130, v138, v188
	s_add_i32 s13, s13, 0
	v_ashrrev_i32_e32 v131, 31, v130
	v_add_u32_e32 v132, v187, v138
	v_add_u32_e32 v128, s13, v180
	v_lshlrev_b64 v[130:131], 11, v[130:131]
	v_ashrrev_i32_e32 v133, 31, v132
	v_readfirstlane_b32 s14, v128
	v_add_u32_e32 v141, s13, v179
	v_lshlrev_b64 v[132:133], 11, v[132:133]
	v_lshl_add_u64 v[130:131], v[136:137], 0, v[130:131]
	s_mov_b32 m0, s14
	v_readfirstlane_b32 s14, v141
	v_add_u32_e32 v142, v186, v138
	v_lshl_add_u64 v[132:133], v[136:137], 0, v[132:133]
	global_load_lds_dwordx4 v[130:131], off
	s_mov_b32 m0, s14
	v_ashrrev_i32_e32 v143, 31, v142
	v_add_u32_e32 v144, v185, v138
	global_load_lds_dwordx4 v[132:133], off
	v_add_u32_e32 v132, s13, v178
	v_lshlrev_b64 v[142:143], 11, v[142:143]
	v_ashrrev_i32_e32 v145, 31, v144
	v_readfirstlane_b32 s14, v132
	v_add_u32_e32 v133, s13, v177
	v_add_u32_e32 v130, v140, v188
	v_lshlrev_b64 v[144:145], 11, v[144:145]
	v_lshl_add_u64 v[142:143], v[136:137], 0, v[142:143]
	s_mov_b32 m0, s14
	v_readfirstlane_b32 s13, v133
	v_ashrrev_i32_e32 v131, 31, v130
	v_add_u32_e32 v128, 0x8000, v128
	v_lshl_add_u64 v[144:145], v[136:137], 0, v[144:145]
	global_load_lds_dwordx4 v[142:143], off
	s_mov_b32 m0, s13
	v_lshlrev_b64 v[130:131], 11, v[130:131]
	v_readfirstlane_b32 s13, v128
	global_load_lds_dwordx4 v[144:145], off
	v_lshl_add_u64 v[130:131], v[134:135], 0, v[130:131]
	s_mov_b32 m0, s13
	v_add_u32_e32 v128, 0x8000, v141
	global_load_lds_dwordx4 v[130:131], off
	v_add_u32_e32 v130, v187, v140
	v_ashrrev_i32_e32 v131, 31, v130
	v_lshlrev_b64 v[130:131], 11, v[130:131]
	v_readfirstlane_b32 s13, v128
	v_lshl_add_u64 v[130:131], v[134:135], 0, v[130:131]
	s_mov_b32 m0, s13
	v_add_u32_e32 v128, 0x8000, v132
	global_load_lds_dwordx4 v[130:131], off
	v_add_u32_e32 v130, v186, v140
	v_ashrrev_i32_e32 v131, 31, v130
	v_lshlrev_b64 v[130:131], 11, v[130:131]
	v_readfirstlane_b32 s13, v128
	v_lshl_add_u64 v[130:131], v[134:135], 0, v[130:131]
	s_mov_b32 m0, s13
	v_add_u32_e32 v128, 0x8000, v133
	global_load_lds_dwordx4 v[130:131], off
	v_add_u32_e32 v130, v185, v140
	v_ashrrev_i32_e32 v131, 31, v130
	v_lshlrev_b64 v[130:131], 11, v[130:131]
	v_readfirstlane_b32 s13, v128
	v_lshl_add_u64 v[130:131], v[134:135], 0, v[130:131]
	s_mov_b32 m0, s13
	s_nop 0
	global_load_lds_dwordx4 v[130:131], off
.LBB0_250:
	s_or_saveexec_b64 s[4:5], s[4:5]
	v_mov_b32_e32 v131, s7
	s_xor_b64 exec, exec, s[4:5]
	s_lshl_b32 s6, s6, 16
	v_mov_b32_e32 v131, s6
	s_or_b64 exec, exec, s[4:5]
	v_add_u32_e32 v128, 0, v131
	v_add_u32_e32 v130, v128, v182
	v_add_u32_e32 v132, v130, v184
	v_add_u32_e32 v128, v128, v183
	ds_read_b128 v[142:145], v132
	ds_read_b128 v[146:149], v132 offset:4096
	ds_read_b128 v[150:153], v132 offset:8192
	ds_read_b128 v[154:157], v132 offset:12288
	v_xad_u32 v132, v184, v233, v128
	ds_read_b128 v[158:161], v132 offset:32768
	v_xor_b32_e32 v230, 0x80, v132
	ds_read_b128 v[162:165], v230 offset:32768
	s_and_b64 s[4:5], exec, s[0:1]
	s_or_b64 s[48:49], s[4:5], s[48:49]
	s_setprio 1
	s_waitcnt lgkmcnt(0)
	v_mfma_f32_32x32x16_bf16 v[112:127], v[142:145], v[158:161], v[112:127]
	v_mfma_f32_32x32x16_bf16 v[96:111], v[142:145], v[162:165], v[96:111]
	v_mfma_f32_32x32x16_bf16 v[80:95], v[146:149], v[158:161], v[80:95]
	v_mfma_f32_32x32x16_bf16 v[64:79], v[146:149], v[162:165], v[64:79]
	v_mfma_f32_32x32x16_bf16 v[48:63], v[150:153], v[158:161], v[48:63]
	v_mfma_f32_32x32x16_bf16 v[32:47], v[150:153], v[162:165], v[32:47]
	v_mfma_f32_32x32x16_bf16 v[16:31], v[154:157], v[158:161], v[16:31]
	v_mfma_f32_32x32x16_bf16 v[0:15], v[154:157], v[162:165], v[0:15]
	s_setprio 0
	v_add_u32_e32 v132, v130, v181
	ds_read_b128 v[142:145], v132
	ds_read_b128 v[146:149], v132 offset:4096
	ds_read_b128 v[150:153], v132 offset:8192
	ds_read_b128 v[154:157], v132 offset:12288
	v_xad_u32 v132, v181, v233, v128
	ds_read_b128 v[158:161], v132 offset:32768
	v_xor_b32_e32 v230, 0x80, v132
	ds_read_b128 v[162:165], v230 offset:32768
	s_setprio 1
	s_waitcnt lgkmcnt(0)
	v_mfma_f32_32x32x16_bf16 v[112:127], v[142:145], v[158:161], v[112:127]
	v_mfma_f32_32x32x16_bf16 v[96:111], v[142:145], v[162:165], v[96:111]
	v_mfma_f32_32x32x16_bf16 v[80:95], v[146:149], v[158:161], v[80:95]
	v_mfma_f32_32x32x16_bf16 v[64:79], v[146:149], v[162:165], v[64:79]
	v_mfma_f32_32x32x16_bf16 v[48:63], v[150:153], v[158:161], v[48:63]
	v_mfma_f32_32x32x16_bf16 v[32:47], v[150:153], v[162:165], v[32:47]
	v_mfma_f32_32x32x16_bf16 v[16:31], v[154:157], v[158:161], v[16:31]
	v_mfma_f32_32x32x16_bf16 v[0:15], v[154:157], v[162:165], v[0:15]
	s_setprio 0
	s_nor_b64 s[4:5], vcc, s[0:1]
	s_and_saveexec_b64 s[0:1], s[4:5]
	s_cbranch_execz .LBB0_241
	v_add_u32_e32 v132, v138, v176
	v_add_u32_e32 v142, v175, v138
	v_add_u32_e32 v144, v174, v138
	v_add_u32_e32 v146, v173, v138
	v_xor_b32_e32 v131, 0x10000, v131
	v_ashrrev_i32_e32 v133, 31, v132
	v_ashrrev_i32_e32 v143, 31, v142
	v_ashrrev_i32_e32 v145, 31, v144
	v_ashrrev_i32_e32 v147, 31, v146
	v_add_u32_e32 v131, 0, v131
	v_lshlrev_b64 v[132:133], 11, v[132:133]
	v_lshlrev_b64 v[142:143], 11, v[142:143]
	v_lshlrev_b64 v[144:145], 11, v[144:145]
	v_lshlrev_b64 v[146:147], 11, v[146:147]
	v_add_u32_e32 v141, v131, v180
	v_lshl_add_u64 v[132:133], v[136:137], 0, v[132:133]
	v_lshl_add_u64 v[142:143], v[136:137], 0, v[142:143]
	v_lshl_add_u64 v[144:145], v[136:137], 0, v[144:145]
	v_lshl_add_u64 v[136:137], v[136:137], 0, v[146:147]
	v_readfirstlane_b32 s4, v141
	v_add_u32_e32 v146, v131, v179
	s_mov_b32 m0, s4
	v_readfirstlane_b32 s4, v146
	global_load_lds_dwordx4 v[132:133], off
	s_mov_b32 m0, s4
	v_add_u32_e32 v132, v140, v176
	global_load_lds_dwordx4 v[142:143], off
	v_add_u32_e32 v142, v131, v178
	v_add_u32_e32 v131, v131, v177
	v_readfirstlane_b32 s4, v142
	s_mov_b32 m0, s4
	v_readfirstlane_b32 s4, v131
	global_load_lds_dwordx4 v[144:145], off
	s_mov_b32 m0, s4
	v_ashrrev_i32_e32 v133, 31, v132
	global_load_lds_dwordx4 v[136:137], off
	v_add_u32_e32 v136, 0x8000, v141
	v_lshlrev_b64 v[132:133], 11, v[132:133]
	v_readfirstlane_b32 s4, v136
	v_lshl_add_u64 v[132:133], v[134:135], 0, v[132:133]
	s_mov_b32 m0, s4
	v_add_u32_e32 v136, 0x8000, v146
	global_load_lds_dwordx4 v[132:133], off
	v_add_u32_e32 v132, v175, v140
	v_ashrrev_i32_e32 v133, 31, v132
	v_lshlrev_b64 v[132:133], 11, v[132:133]
	v_readfirstlane_b32 s4, v136
	v_lshl_add_u64 v[132:133], v[134:135], 0, v[132:133]
	s_mov_b32 m0, s4
	v_add_u32_e32 v136, 0x8000, v142
	global_load_lds_dwordx4 v[132:133], off
	v_add_u32_e32 v132, v174, v140
	v_ashrrev_i32_e32 v133, 31, v132
	v_lshlrev_b64 v[132:133], 11, v[132:133]
	v_readfirstlane_b32 s4, v136
	v_lshl_add_u64 v[132:133], v[134:135], 0, v[132:133]
	s_mov_b32 m0, s4
	v_add_u32_e32 v131, 0x8000, v131
	global_load_lds_dwordx4 v[132:133], off
	v_add_u32_e32 v132, v173, v140
	v_ashrrev_i32_e32 v133, 31, v132
	v_lshlrev_b64 v[132:133], 11, v[132:133]
	v_readfirstlane_b32 s4, v131
	v_lshl_add_u64 v[132:133], v[134:135], 0, v[132:133]
	s_mov_b32 m0, s4
	s_nop 0
	global_load_lds_dwordx4 v[132:133], off
	s_branch .LBB0_241
